# attention prompt-unit output rows stored through a per-wave LDS transpose (4 coalesced dwordx4 instead of 8 row-per-lane dwordx2)
# speedup vs baseline: 1.0581x; 1.0025x over previous
; __device__ __forceinline__ unsigned pk(float lo, float hi) { return pg8::cvt_pk_bf16(lo, hi); }
; __device__ __forceinline__ void attn_unit_prompt(const Args& a, LAS unsigned char* lds, int b, int h, int qb) {
;     ...
;     lrun += __shfl_xor(lrun, 32);
;     const float inv = 1.f / lrun;
;     bf16_t* og = (bf16_t*)(a.ws + WS_OG) + qrow * DM + h * 64;
; #pragma unroll
;     for (int db = 0; db < 2; ++db)
; #pragma unroll
;         for (int j = 0; j < 4; ++j) { u32x2 o; o.x = pk(ot[db][4 * j] * inv, ot[db][4 * j + 1] * inv); o.y = pk(ot[db][4 * j + 2] * inv, ot[db][4 * j + 3] * inv);
;             *(u32x2*)(og + 32 * db + 8 * j + 4 * hi) = o; }
.LBB0_1715:
	v_and_b32_e32 v36, 64, v150
	v_xor_b32_e32 v35, 32, v150
	v_add_u32_e32 v36, 64, v36
	v_cmp_lt_i32_e32 vcc, v35, v36
	v_ashrrev_i32_e32 v121, 31, v120
	s_waitcnt vmcnt(0)
	s_waitcnt vmcnt(0)
	s_waitcnt vmcnt(0)
	v_mov_b32_e32 v69, v67
	v_cndmask_b32_e32 v35, v150, v35, vcc
	v_lshlrev_b32_e32 v35, 2, v35
	ds_bpermute_b32 v35, v35, v34
	s_add_i32 s56, s56, 1
	s_cmp_eq_u32 s56, 4
	s_waitcnt lgkmcnt(0)
	v_add_f32_e32 v34, v34, v35
	v_div_scale_f32 v35, s[0:1], v34, v34, 1.0
	v_rcp_f32_e32 v36, v35
	s_nop 0
	v_fma_f32 v37, -v35, v36, 1.0
	v_fmac_f32_e32 v36, v37, v36
	v_div_scale_f32 v37, vcc, 1.0, v34, 1.0
	v_mul_f32_e32 v38, v37, v36
	v_fma_f32 v39, -v35, v38, v37
	v_fmac_f32_e32 v38, v39, v36
	v_fma_f32 v35, -v35, v38, v37
	v_div_fmas_f32 v35, v35, v36, v38
	v_div_fixup_f32 v36, v35, v34, 1.0
	v_mul_f32_e32 v34, v2, v36
	v_mul_f32_e32 v35, v3, v36
	v_mul_f32_e32 v37, v4, v36
	v_mul_f32_e32 v38, v5, v36
	v_cvt_pk_bf16_f32 v2, v34, v35
	v_cvt_pk_bf16_f32 v3, v37, v38
	v_mul_f32_e32 v34, v6, v36
	v_mul_f32_e32 v35, v7, v36
	v_mul_f32_e32 v37, v8, v36
	v_mul_f32_e32 v38, v9, v36
	v_cvt_pk_bf16_f32 v4, v34, v35
	v_cvt_pk_bf16_f32 v5, v37, v38
	v_mul_f32_e32 v34, v10, v36
	v_mul_f32_e32 v35, v11, v36
	v_mul_f32_e32 v37, v12, v36
	v_mul_f32_e32 v38, v13, v36
	v_cvt_pk_bf16_f32 v6, v34, v35
	v_cvt_pk_bf16_f32 v7, v37, v38
	v_mul_f32_e32 v34, v14, v36
	v_mul_f32_e32 v35, v15, v36
	v_mul_f32_e32 v37, v16, v36
	v_mul_f32_e32 v38, v17, v36
	v_cvt_pk_bf16_f32 v8, v34, v35
	v_cvt_pk_bf16_f32 v9, v37, v38
	v_mul_f32_e32 v34, v18, v36
	v_mul_f32_e32 v35, v19, v36
	v_mul_f32_e32 v37, v20, v36
	v_mul_f32_e32 v38, v21, v36
	v_cvt_pk_bf16_f32 v10, v34, v35
	v_cvt_pk_bf16_f32 v11, v37, v38
	v_mul_f32_e32 v34, v22, v36
	v_mul_f32_e32 v35, v23, v36
	v_mul_f32_e32 v37, v24, v36
	v_mul_f32_e32 v38, v25, v36
	v_cvt_pk_bf16_f32 v12, v34, v35
	v_cvt_pk_bf16_f32 v13, v37, v38
	v_mul_f32_e32 v34, v26, v36
	v_mul_f32_e32 v35, v27, v36
	v_mul_f32_e32 v37, v28, v36
	v_mul_f32_e32 v38, v29, v36
	v_cvt_pk_bf16_f32 v14, v34, v35
	v_cvt_pk_bf16_f32 v15, v37, v38
	v_mul_f32_e32 v34, v30, v36
	v_mul_f32_e32 v35, v31, v36
	v_mul_f32_e32 v37, v32, v36
	v_mul_f32_e32 v38, v33, v36
	v_cvt_pk_bf16_f32 v16, v34, v35
	v_cvt_pk_bf16_f32 v17, v37, v38
	v_and_b32_e32 v18, 63, v0
	v_lshrrev_b32_e32 v21, 6, v0
	v_mul_u32_u24_e32 v21, 0x900, v21
	v_add_u32_e32 v21, 0x21000, v21
	v_and_b32_e32 v36, 31, v18
	v_mul_u32_u24_e32 v19, 72, v36
	v_lshrrev_b32_e32 v20, 5, v18
	v_lshl_add_u32 v19, v20, 3, v19
	v_add_u32_e32 v19, v21, v19
	v_lshrrev_b32_e32 v20, 2, v18
	v_sub_u32_e32 v37, v20, v36
	v_add_u32_e32 v37, v120, v37
	v_mul_u32_u24_e32 v20, 72, v20
	v_and_b32_e32 v18, 3, v18
	v_lshl_add_u32 v20, v18, 4, v20
	v_add_u32_e32 v20, v21, v20
	v_lshlrev_b32_e32 v22, 4, v18
	v_mov_b32_e32 v23, 0
	v_mov_b32_e32 v24, v37
	v_mov_b32_e32 v25, 0
	v_add_u32_e32 v26, 16, v37
	v_mov_b32_e32 v27, 0
	v_lshlrev_b64 v[24:25], 11, v[24:25]
	v_lshlrev_b64 v[26:27], 11, v[26:27]
	v_lshl_add_u64 v[24:25], s[24:25], 0, v[24:25]
	v_lshl_add_u64 v[26:27], s[24:25], 0, v[26:27]
	v_lshl_add_u64 v[24:25], v[24:25], 0, v[22:23]
	v_lshl_add_u64 v[26:27], v[26:27], 0, v[22:23]
	ds_write_b64 v19, v[2:3]
	ds_write_b64 v19, v[4:5] offset:16
	ds_write_b64 v19, v[6:7] offset:32
	ds_write_b64 v19, v[8:9] offset:48
	ds_read2_b64 v[28:31], v20 offset1:1
	ds_read2_b64 v[32:35], v20 offset0:144 offset1:145
	s_waitcnt lgkmcnt(0)
	global_store_dwordx4 v[24:25], v[28:31], off
	global_store_dwordx4 v[26:27], v[32:35], off
	s_nop 1
	ds_write_b64 v19, v[10:11]
	ds_write_b64 v19, v[12:13] offset:16
	ds_write_b64 v19, v[14:15] offset:32
	ds_write_b64 v19, v[16:17] offset:48
	ds_read2_b64 v[28:31], v20 offset1:1
	ds_read2_b64 v[32:35], v20 offset0:144 offset1:145
	s_waitcnt lgkmcnt(0)
	global_store_dwordx4 v[24:25], v[28:31], off offset:64
	global_store_dwordx4 v[26:27], v[32:35], off offset:64
	s_cbranch_scc1 .LBB0_1634
